# P4 rebalanced: workgroups 0-127 (compress + pool units) additionally quantise the last 3072 FFN2 gate|up items through the G<=128 gu_quant instance; workgroups 128-255 do the rest; on top of v015
# baseline (speedup 1.0000x reference)
; #define LAS __attribute__((address_space(3)))
;     const int lane = (F.tid & 63), stride = nworkers * 8, first = lo + worker * 8 + F.wave;
;     LAS unsigned* T = (LAS unsigned*)(F.lds + F.wave * 16384);
;     if (first >= hi) return;
;     const int n_my = (hi - first + stride - 1) / stride;
; __global__ void __launch_bounds__(512, 2) mk_fwd(Args args) {
;     ...
;         if (F.G > 128) { if ((int)blockIdx.x >= 128) gu_quant(F, P0_R_GU2 + 9000, P0_R_D1, (int)blockIdx.x - 128, F.G - 128); }
;         else gu_quant(F, P0_R_GU2 + 9000, P0_R_D1, (int)blockIdx.x, F.G);
.LBB0_2519:
	s_cmpk_lt_i32 s69, 0x80
	s_mov_b64 s[0:1], -1
	s_waitcnt lgkmcnt(0)
	s_barrier
	s_cbranch_scc0 .LBB0_2571
	s_lshl_b32 s0, s69, 3
	s_add_i32 s30, s0, s68
	s_add_i32 s30, s30, 0xa000
	s_cmp_gt_i32 s30, 0xabff
	s_cbranch_scc1 .LBB0_2570
	s_movk_i32 s31, 0x400
	s_abs_i32 s3, s31
	v_cvt_f32_u32_e32 v1, s3
	s_sub_i32 s2, s31, s30
	s_add_i32 s0, s2, 0xabff
	s_sub_i32 s2, 0xffff5401, s2
	v_rcp_iflag_f32_e32 v1, v1
	s_sub_i32 s4, 0, s3
	s_max_i32 s6, s0, s2
	s_add_i32 s1, s30, 0x2aff
	v_mul_f32_e32 v1, 0x4f7ffffe, v1
	v_cvt_u32_f32_e32 v1, v1
	s_nop 0
	v_readfirstlane_b32 s2, v1
	s_mul_i32 s4, s4, s2
	s_mul_hi_u32 s4, s2, s4
	s_add_i32 s2, s2, s4
	s_mul_hi_u32 s7, s6, s2
	s_cmpk_lt_u32 s1, 0x55ff
	s_mov_b32 s1, 0x27c10
	s_cbranch_scc1 .LBB0_2523
	s_add_i32 s1, s30, 0xffffd500
	s_add_i32 s2, s30, 0xffffaa00
	s_cmpk_lt_u32 s2, 0x2b00
	s_mov_b32 s2, 0x27c90
	s_cselect_b32 s2, s2, 0x27c98
	s_cmpk_gt_u32 s1, 0x2aff
	s_cselect_b32 s1, s2, 0x27c18

; #define LAS __attribute__((address_space(3)))
;     const int lane = (F.tid & 63), stride = nworkers * 8, first = lo + worker * 8 + F.wave;
;     LAS unsigned* T = (LAS unsigned*)(F.lds + F.wave * 16384);
;     if (first >= hi) return;
;     const int n_my = (hi - first + stride - 1) / stride;
; __global__ void __launch_bounds__(512, 2) mk_fwd(Args args) {
;     ...
;         if (F.G > 128) { if ((int)blockIdx.x >= 128) gu_quant(F, P0_R_GU2 + 9000, P0_R_D1, (int)blockIdx.x - 128, F.G - 128); }
.LBB0_2571:
	s_andn2_b64 vcc, exec, s[0:1]
	s_cbranch_vccnz .LBB0_2623
	s_cmpk_lt_i32 s69, 0x80
	s_cbranch_scc1 .LBB0_2623
	s_lshl_b32 s0, s69, 3
	s_add_i32 s30, s0, s68
	s_addk_i32 s30, 0x7528
	s_cmp_gt_i32 s30, 0x9fff
	s_cbranch_scc1 .LBB0_2623
	s_lshl_b32 s0, s71, 3
	s_add_i32 s31, s0, 0xfffffc00
	s_sub_i32 s1, 0x400, s0
	s_max_i32 s3, s31, s1
	v_cvt_f32_u32_e32 v1, s3
	s_sub_i32 s2, s0, s30
	s_add_i32 s0, s2, 0x9bff
	s_sub_i32 s2, 0xffff6401, s2
	v_rcp_iflag_f32_e32 v1, v1
	s_max_i32 s6, s0, s2
	s_sub_i32 s2, 0, s3
	s_add_i32 s1, s30, 0x2aff
	v_mul_f32_e32 v1, 0x4f7ffffe, v1
	v_cvt_u32_f32_e32 v1, v1
	s_nop 0
	v_readfirstlane_b32 s4, v1
	s_mul_i32 s2, s2, s4
	s_mul_hi_u32 s2, s4, s2
	s_add_i32 s4, s4, s2
	s_mul_hi_u32 s7, s6, s4
	s_cmpk_lt_u32 s1, 0x55ff
	s_mov_b32 s1, 0x27c10
	s_cbranch_scc1 .LBB0_2576
	s_add_i32 s1, s30, 0xffffd500
	s_add_i32 s2, s30, 0xffffaa00
	s_cmpk_lt_u32 s2, 0x2b00
	s_mov_b32 s2, 0x27c90
	s_cselect_b32 s2, s2, 0x27c98
	s_cmpk_gt_u32 s1, 0x2aff
	s_cselect_b32 s1, s2, 0x27c18
